# v132 with grid-barrier flag poll spinning without s_sleep
# speedup vs baseline: 1.0186x; 1.0186x over previous
.LBB0_73:
	s_nop 0
	global_load_dword v2, v1, s[2:3] offset:32 sc1
	s_waitcnt vmcnt(0)
	v_and_b32_e32 v2, 0xffff0000, v2
	v_cmp_ne_u32_e32 vcc, v2, v0
	s_or_b64 s[22:23], vcc, s[22:23]
	s_andn2_b64 exec, exec, s[22:23]
	s_cbranch_execnz .LBB0_73
